# attention: wave-priority asymmetry (setprio 1 on waves 4-7) removed, on top of v55
# speedup vs baseline: 1.0146x; 1.0146x over previous
; #define WAIT_BAR(N) asm volatile("s_waitcnt vmcnt(" #N ") lgkmcnt(0)\n\ts_barrier":::"memory")
; __device__ __forceinline__ int t5_bucket(int d){ if(d<16)return d; int b=16+(int)(__builtin_log2f((float)d*(1.0f/16.0f))*(16.0f/3.0f)); return b>31?31:b; }
; template<int THRL> __device__ __forceinline__ void attn_unit(int b,int h,int qb,const AttnArgs&A,char*shm,bool setup){
;     ...
;   const long rowbase=(long)b*SEQ; const int q0=qb*QB; const int qw0=q0+rg*QBLK;
;   const bf16raw*Qw=A.P+(rowbase+qw0)*PITCH+(2*h+mp)*64;
;   const unsigned char*imgS=A.KV+((size_t)((b*NHEAD+h)*(SEQ/KVBLK))<<15);
;   const unsigned voff=(unsigned)(wid*1024+lane*16);
;   const unsigned lds0=(unsigned)(uintptr_t)shm;
;   float*wsf=(float*)(shm+LDS_WS)+wid*64;
;   float*biasT=(float*)(shm+LDS_BIAS);
;   float*xch=(float*)shm+rg*4096+lane;
;   const lds_cptr shm3=(lds_cptr)shm;
;   float*subgT=biasT+256;
;   if(setup){
;     if(tid<256){ const int m_=tid>>7,d=tid&127; biasT[tid]=A.relb[t5_bucket(d)*16+2*h+m_]*LOG2E; }
;     else if(tid<384){ subgT[tid-256]=A.subg[tid-256]*A.onem; }
;     asm volatile("s_waitcnt vmcnt(0) lgkmcnt(0)\n\ts_barrier":::"memory");
;   }
;   const float cfar=biasT[mp*128+127];
;   const unsigned kdst=lds0+LDS_KR+wid*1024, vdst=lds0+LDS_VR+wid*1024, ddst=lds0+LDS_DUMMY+wid*1024;
;     ...
;   const lds_cptr kp0=shm3+LDS_KR+mp*8192+hi*1024+r32*16;
;   const lds_cptr vp0=shm3+LDS_VR+hi*512+r32*16;
;   const int NT=(q0+QB)/KVBLK;
;   bf16x8 qr[4];
;   #pragma unroll
;   for(int d0=0;d0<4;++d0)qr[d0]=*reinterpret_cast<const bf16x8*>(&Qw[(long)r32*PITCH+d0*16+hi*8]);
;   DMA_K(0,0); DMA_V(0,0); DMA_K(1,SLOT16);
;   DMA_V(1,SLOT16); { const unsigned char*g_=imgS+((size_t)(NT>2?2:NT-1)<<15); const unsigned d_=(unsigned)__builtin_amdgcn_readfirstlane(NT>2?kdst+2*SLOT16:ddst); glds16s(g_,voff,d_); glds16s(g_+8192,voff,d_+8192); }
;   float mhat=0.f,l=0.f;
;   f32x16 o[4];
;   #pragma unroll
;   for(int d0=0;d0<4;++d0)o[d0]=f32x16{};
;   const int qpos=qw0+r32;
;   f32x16 p0,p1; u32x4 pw[4]; bf16x8 kf[8]; bf16x8 va[4],vb[4];
;   f32x16 cini;
;   #pragma unroll
;   for(int r=0;r<16;++r)cini[r]=cfar;
;   asm volatile("":"+v"(cini));
;     ...
;   WAIT_BAR(8);
.LBB0_235:
	s_lshl_b32 s9, s55, 3
	s_or_b32 s20, s9, 15
	s_and_b32 s8, s55, 1
	s_sub_i32 s20, s20, s58
	s_or_b32 s9, s9, s58
	s_cmp_eq_u32 s8, 0
	s_cselect_b32 s8, s9, s20
	s_ashr_i32 s20, s28, 6
	s_and_b32 s52, s20, 3
	s_lshl_b32 s22, s8, 7
	s_lshl_b32 s23, s52, 5
	s_or_b32 s40, s23, s22
	s_ashr_i32 s47, s28, 8
	s_ashr_i32 s8, s40, 31
	s_add_u32 s26, s38, s40
	s_addc_u32 s27, s39, s8
	s_lshl_b64 s[8:9], s[26:27], 12
	s_add_u32 s21, s78, s8
	s_addc_u32 s29, s79, s9
	s_add_i32 s8, s47, s53
	s_lshl_b32 s8, s8, 6
	s_ashr_i32 s9, s8, 31
	v_and_b32_e32 v208, 31, v2
	s_lshl_b64 s[8:9], s[8:9], 1
	v_bfe_u32 v206, v2, 5, 1
	s_add_u32 s8, s21, s8
	v_lshlrev_b32_e32 v0, 12, v208
	s_addc_u32 s9, s29, s9
	v_lshl_or_b32 v0, v206, 4, v0
	global_load_dwordx4 v[130:133], v0, s[8:9]
	global_load_dwordx4 v[134:137], v0, s[8:9] offset:32
	global_load_dwordx4 v[138:141], v0, s[8:9] offset:64
	global_load_dwordx4 v[142:145], v0, s[8:9] offset:96
	s_lshl_b32 s8, s47, 9
	s_add_i32 s29, s8, 0
	s_lshl_b32 s41, s20, 10
	s_add_i32 s29, s29, 0x18800
	s_cmp_lg_u32 0, -1
	s_cselect_b32 s8, 0, 0
	v_and_b32_e32 v207, 63, v2
	v_mov_b32_e32 v0, s29
	s_add_i32 s46, s41, s8
	s_add_i32 s8, s22, 0x80
	v_lshl_or_b32 v209, v207, 4, s41
	s_waitcnt vmcnt(19)
	ds_read_b32 v64, v0 offset:508
	s_ashr_i32 s72, s8, 6
	s_mov_b32 s8, m0
	s_mov_b32 m0, s46
	s_nop 0
	global_load_lds_dwordx4 v209, s[42:43]
	s_mov_b32 m0, s8
	s_add_i32 s8, s46, 0x2000
	s_mov_b32 s9, m0
	s_mov_b32 m0, s8
	s_nop 0
	global_load_lds_dwordx4 v209, s[30:31]
	s_mov_b32 m0, s9
	s_add_i32 s99, s46, 0xc000
	s_mov_b32 s8, m0
	s_mov_b32 m0, s99
	s_nop 0
	global_load_lds_dwordx4 v209, s[34:35]
	s_mov_b32 m0, s8
	s_add_i32 s8, s46, 0xe000
	s_mov_b32 s9, m0
	s_mov_b32 m0, s8
	s_nop 0
	global_load_lds_dwordx4 v209, s[92:93]
	s_mov_b32 m0, s9
	s_add_i32 s8, s46, 0x4000
	s_mov_b32 s9, m0
	s_mov_b32 m0, s8
	s_nop 0
	global_load_lds_dwordx4 v209, s[96:97]
	s_mov_b32 m0, s9
	s_add_i32 s8, s46, 0x6000
	s_mov_b32 s9, m0
	s_mov_b32 m0, s8
	s_nop 0
	global_load_lds_dwordx4 v209, s[4:5]
	s_mov_b32 m0, s9
	s_add_i32 s8, s46, 0x10000
	s_mov_b32 s9, m0
	s_mov_b32 m0, s8
	s_nop 0
	global_load_lds_dwordx4 v209, s[6:7]
	s_mov_b32 m0, s9
	s_add_i32 s8, s46, 0x12000
	s_add_i32 s81, s72, -1
	s_mov_b32 s9, m0
	s_mov_b32 m0, s8
	s_nop 0
	global_load_lds_dwordx4 v209, s[12:13]
	s_mov_b32 m0, s9
	s_min_i32 s8, s81, 2
	s_ashr_i32 s9, s8, 31
	s_add_i32 s98, s46, 0x19000
	s_lshl_b64 s[8:9], s[8:9], 15
	s_add_u32 s8, s42, s8
	s_addc_u32 s9, s43, s9
	s_add_i32 s20, s46, 0x8000
	s_cmp_gt_i32 s72, 2
	s_cselect_b64 vcc, -1, 0
	s_waitcnt lgkmcnt(0)
	v_mov_b32_e32 v78, v64
	v_mov_b32_e32 v79, v64
	s_and_b64 s[82:83], vcc, exec
	v_mov_b32_e32 v65, v64
	v_mov_b32_e32 v66, v64
	v_mov_b32_e32 v67, v64
	v_mov_b32_e32 v68, v64
	v_mov_b32_e32 v69, v64
	v_mov_b32_e32 v70, v64
	v_mov_b32_e32 v71, v64
	v_mov_b32_e32 v72, v64
	v_mov_b32_e32 v73, v64
	v_mov_b32_e32 v74, v64
	v_mov_b32_e32 v75, v64
	v_mov_b32_e32 v76, v64
	v_mov_b32_e32 v77, v64
	s_waitcnt vmcnt(9)
	v_mov_b64_e32 v[112:113], v[78:79]
	s_cselect_b32 s20, s20, s98
	s_mov_b32 s21, m0
	s_mov_b32 m0, s20
	s_nop 0
	global_load_lds_dwordx4 v209, s[8:9]
	s_mov_b32 m0, s21
	s_add_u32 s82, s8, 0x2000
	v_mov_b64_e32 v[110:111], v[76:77]
	v_mov_b64_e32 v[108:109], v[74:75]
	v_mov_b64_e32 v[106:107], v[72:73]
	v_mov_b64_e32 v[104:105], v[70:71]
	v_mov_b64_e32 v[102:103], v[68:69]
	v_mov_b64_e32 v[100:101], v[66:67]
	v_mov_b64_e32 v[98:99], v[64:65]
	s_addc_u32 s83, s9, 0
	s_addk_i32 s20, 0x2000
	s_mov_b32 s21, m0
	s_mov_b32 m0, s20
	s_nop 0
	global_load_lds_dwordx4 v209, s[82:83]
	s_mov_b32 m0, s21
	s_waitcnt vmcnt(8) lgkmcnt(0)
	s_barrier
; #define SBAR() __builtin_amdgcn_sched_barrier(0)
; #define WAIT_BAR(N) asm volatile("s_waitcnt vmcnt(" #N ") lgkmcnt(0)\n\ts_barrier":::"memory")
;   #define KRD(kp_) do{ _Pragma("unroll") for(int d0_=0;d0_<4;++d0_){ kf[2*d0_]=LDK(kp_,d0_*2048); kf[2*d0_+1]=LDK(kp_,d0_*2048+512); } }while(0)
;   #define VRK(dst,vp_,ks_) do{ _Pragma("unroll") for(int d0_=0;d0_<4;++d0_){ dst[d0_]=*(const __attribute__((address_space(3))) bf16x8*)((vp_)+d0_*4096+(ks_)*1024); } }while(0)
; template<int THRL> __device__ __forceinline__ void attn_unit(int b,int h,int qb,const AttnArgs&A,char*shm,bool setup){
;     ...
;   KRD(kp0);
;   int ks_t=0,ks_n=SLOT16,vs_t=0,vs_nn=2*SLOT16;
;   for(int t=0;t<NT;++t){
;     WAIT_BAR(4);
;     const int kv0=t*KVBLK;
;     const bool act=(kv0<=qw0+QBLK-1);
;     const bool actn=(t+1<NT)&&(kv0+KVBLK<=qw0+QBLK-1);
;     const lds_cptr vp=vp0+vs_t;
;     const bool dk=(t+3<NT), dv=(t+2<NT);
;     const unsigned char*gk_=imgS+((size_t)(dk?t+3:NT-1)<<15); const unsigned char*gv_=imgS+((size_t)(dv?t+2:NT-1)<<15)+16384;
;     const unsigned kd_=(unsigned)__builtin_amdgcn_readfirstlane(dk?kdst+ks_t:ddst), vd_=(unsigned)__builtin_amdgcn_readfirstlane(dv?vdst+vs_nn:ddst);
;     if(act){
;       VRK(va,vp,0); VRK(vb,vp,1);
;       SBAR();
;       QKM(cini);
;     }
;     if(act){
;       const bool far=(qw0-(kv0+63)>=113);
;       if(!far){ const float*bt=biasT+mp*128; const int dq=qpos-kv0-4*hi;
;         #pragma unroll
;         for(int r=0;r<16;++r){ const int d=dq-((r&3)+8*(r>>2));
;           const int i0=d<0?0:(d>127?127:d);
;           const float b0=bt[i0];
;           const float n0=d>=0?0.f:-INFINITY;
;           p0[r]=(p0[r]+(b0-cfar))+n0; if((r&7)==7)asm volatile("":::"memory"); }
;         #pragma unroll
;         for(int r=0;r<16;++r){ const int d1=dq-32-((r&3)+8*(r>>2));
;           const int i1=d1<0?0:(d1>127?127:d1);
;           const float b1=bt[i1];
;           const float n1=d1>=0?0.f:-INFINITY;
;           p1[r]=(p1[r]+(b1-cfar))+n1; if((r&7)==7)asm volatile("":::"memory"); } }
	s_cmp_lt_i32 s72, 1
	s_cbranch_scc1 .LBB0_251
	s_lshl_b32 s20, s47, 13
	v_lshlrev_b32_e32 v0, 10, v206
	v_lshlrev_b32_e32 v2, 4, v208
	s_add_i32 s20, s20, 0
	v_add3_u32 v65, s20, v0, v2
	ds_read_b128 v[114:117], v65
	ds_read_b128 v[118:121], v65 offset:512
	ds_read_b128 v[122:125], v65 offset:2048
	ds_read_b128 v[126:129], v65 offset:2560
	ds_read_b128 v[146:149], v65 offset:4096
	ds_read_b128 v[150:153], v65 offset:4608
	ds_read_b128 v[154:157], v65 offset:6144
	ds_read_b128 v[158:161], v65 offset:6656
	s_cmp_gt_u32 s72, 3
	s_cselect_b32 s82, s46, s98
	s_cmp_lg_u32 0, -1
	s_cselect_b32 s20, 0, 0
	s_add_i32 s20, s20, s41
	s_waitcnt vmcnt(4) lgkmcnt(0)
	s_barrier
	s_add_i32 s20, s20, 0x14000
	v_lshlrev_b32_e32 v3, 9, v206
	s_and_b64 s[94:95], vcc, exec
	v_add3_u32 v210, 0, v3, v2
	v_lshlrev_b32_e32 v212, 2, v206
	s_cselect_b32 s73, s20, s98
	s_cmp_gt_i32 s22, -1
	s_mov_b64 vcc, -1
	s_cbranch_scc0 .LBB0_240
	ds_read_b128 v[42:45], v210 offset:49152
	ds_read_b128 v[174:177], v210 offset:50176
	ds_read_b128 v[38:41], v210 offset:53248
	ds_read_b128 v[170:173], v210 offset:54272
	ds_read_b128 v[34:37], v210 offset:57344
	ds_read_b128 v[166:169], v210 offset:58368
	ds_read_b128 v[178:181], v210 offset:61440
	ds_read_b128 v[162:165], v210 offset:62464
	s_sub_i32 s20, s40, 63
	s_waitcnt lgkmcnt(14)
	v_mfma_f32_32x32x16_bf16 v[18:33], v[114:117], v[130:133], v[98:113]
	s_cmpk_gt_i32 s20, 0x70
	v_mfma_f32_32x32x16_bf16 v[2:17], v[118:121], v[130:133], v[98:113]
	s_waitcnt lgkmcnt(12)
	v_mfma_f32_32x32x16_bf16 v[2:17], v[126:129], v[134:137], v[2:17]
	v_mfma_f32_32x32x16_bf16 v[18:33], v[122:125], v[134:137], v[18:33]
	s_waitcnt lgkmcnt(10)
	v_mfma_f32_32x32x16_bf16 v[2:17], v[150:153], v[138:141], v[2:17]
	v_mfma_f32_32x32x16_bf16 v[18:33], v[146:149], v[138:141], v[18:33]
	s_waitcnt lgkmcnt(8)
	v_mfma_f32_32x32x16_bf16 v[2:17], v[158:161], v[142:145], v[2:17]
	v_mfma_f32_32x32x16_bf16 v[18:33], v[154:157], v[142:145], v[18:33]
	s_cbranch_scc1 .LBB0_239
	v_or_b32_e32 v0, s40, v208
	v_sub_u32_e32 v0, v0, v212
	s_sub_i32 s20, s29, 0x18800
	s_lshl_b32 s20, s20, 1
	s_add_i32 s20, s20, 0x1d000
	v_lshl_add_u32 v82, v0, 2, s20
	ds_read2_b32 v[46:47], v82 offset0:63 offset1:62
	ds_read2_b32 v[48:49], v82 offset0:61 offset1:60
	ds_read2_b32 v[50:51], v82 offset0:55 offset1:54
	ds_read2_b32 v[52:53], v82 offset0:53 offset1:52
	ds_read2_b32 v[54:55], v82 offset0:47 offset1:46
	ds_read2_b32 v[56:57], v82 offset0:45 offset1:44
	ds_read2_b32 v[58:59], v82 offset0:39 offset1:38
	ds_read2_b32 v[60:61], v82 offset0:37 offset1:36
	ds_read2_b32 v[66:67], v82 offset0:31 offset1:30
	ds_read2_b32 v[68:69], v82 offset0:29 offset1:28
	ds_read2_b32 v[70:71], v82 offset0:23 offset1:22
	ds_read2_b32 v[72:73], v82 offset0:21 offset1:20
	ds_read2_b32 v[74:75], v82 offset0:15 offset1:14
	ds_read2_b32 v[76:77], v82 offset0:13 offset1:12
	ds_read2_b32 v[78:79], v82 offset0:7 offset1:6
	ds_read2_b32 v[80:81], v82 offset0:5 offset1:4
	s_waitcnt lgkmcnt(8)
	v_pk_add_f32 v[18:19], v[18:19], v[46:47]
	v_pk_add_f32 v[20:21], v[20:21], v[48:49]
	v_pk_add_f32 v[22:23], v[22:23], v[50:51]
	v_pk_add_f32 v[24:25], v[24:25], v[52:53]
	v_pk_add_f32 v[26:27], v[26:27], v[54:55]
	v_pk_add_f32 v[28:29], v[28:29], v[56:57]
	v_pk_add_f32 v[30:31], v[30:31], v[58:59]
	v_pk_add_f32 v[32:33], v[32:33], v[60:61]
	s_waitcnt lgkmcnt(0)
	v_pk_add_f32 v[2:3], v[2:3], v[66:67]
	v_pk_add_f32 v[4:5], v[4:5], v[68:69]
	v_pk_add_f32 v[6:7], v[6:7], v[70:71]
	v_pk_add_f32 v[8:9], v[8:9], v[72:73]
	v_pk_add_f32 v[10:11], v[10:11], v[74:75]
	v_pk_add_f32 v[12:13], v[12:13], v[76:77]
	v_pk_add_f32 v[14:15], v[14:15], v[78:79]
	v_pk_add_f32 v[16:17], v[16:17], v[80:81]
